# prompt-row rs2 (ffn norm statistic) computed by the workgroups idle in the up-GEMM's partial last round instead of in its own phase; on top of v11 (attention Y-phase rewrite + LDS-DMA loads spread)
# baseline (speedup 1.0000x reference)
; #define LAS __attribute__((address_space(3)))
; #define GLDS16(gsrc, ldst) __builtin_amdgcn_global_load_lds((const unsigned*)(gsrc), (LAS unsigned*)(ldst), 16, 0, 0)
; template <bool MLA>
; DI void attn_load_tile(LAS unsigned char* buf, const bf16* Kp, int kstride, const bf16* KRp, const bf16* Vp, int vstride, int t, int wave, const AttnOffs& o) {
;     const char* kt = (const char*)(Kp + (size_t)t * 64 * kstride); const char* vt = (const char*)(Vp + (size_t)t * 64 * vstride);
; #pragma unroll
;     for (int i = 0; i < 2; ++i) {
;         GLDS16(kt + o.k[i], buf + (2 * wave + i) * 1024);
;         GLDS16(vt + o.v[i], buf + AT_V + (2 * wave + i) * 1024);
;     }
;     if (MLA) { const char* rt = (const char*)(KRp + (size_t)t * 64 * 64); GLDS16(rt + o.kr, buf + AT_KR + wave * 1024); }
; template <bool MLA>
; DI void attn_unit(LAS unsigned char* lds, const bf16* Qp, int qstride, const bf16* Kp, int kstride, const bf16* KRp, const bf16* Vp, int vstride,
;                   bf16* Op, int ostride, int t_lo, int t_hi, int qc, bool active, int wave, int lane) {
;     ...
;         if (pre) attn_load_tile<MLA>(nbuf, Kp, kstride, KRp, Vp, vstride, t + 2, wave, offs);
;         if (doit) {
;             float mx = s0[0];
; #pragma unroll
;             for (int i = 1; i < 16; ++i) mx = fmaxf(mx, s0[i]);
; #pragma unroll
;             for (int i = 0; i < 16; ++i) mx = fmaxf(mx, s1[i]);
;             mx = fmaxf(mx, __shfl_xor(mx, 32));
;             const float m_new = fmaxf(m_run, mx);
;             const float alpha = __builtin_amdgcn_exp2f(m_run - m_new);
;             m_run = m_new;
;             float ps = 0.f;
; #pragma unroll
;             for (int i = 0; i < 16; ++i) { s0[i] = __builtin_amdgcn_exp2f(s0[i] - m_new); s1[i] = __builtin_amdgcn_exp2f(s1[i] - m_new); ps += s0[i] + s1[i]; }
;             l_run = l_run * alpha + ps;
; #pragma unroll
;             for (int d = 0; d < 4; ++d)
; #pragma unroll
;                 for (int i = 0; i < 16; ++i) o[d][i] *= alpha;
.LBB0_855:
	s_add_i32 s96, s96, 0xffff6000
	s_cmp_lg_u32 s93, 0
	s_cselect_b32 s96, s96, 0x14000
	s_add_i32 s98, s96, s69
	s_add_i32 s99, s96, s70
	s_add_i32 s99, s99, 0x8000
	s_mov_b32 s100, 0x9b40000
	s_mov_b32 s101, 0
	s_andn2_b64 vcc, exec, s[58:59]
	s_cbranch_vccz .Lmla_y_pre
	v_lshl_add_u64 v[2:3], s[28:29], 0, v[218:219]
	s_mov_b32 m0, s98
	s_nop 0
	global_load_lds_dwordx4 v[2:3], off
	v_lshl_add_u64 v[2:3], s[28:29], 0, v[220:221]
	v_lshl_add_u64 v[4:5], v[2:3], 0, s[100:101]
	s_add_i32 m0, s98, 0x4000
	v_lshl_add_u64 v[2:3], v[2:3], 0, s[44:45]
	global_load_lds_dwordx4 v[4:5], off
	v_lshl_add_u64 v[4:5], s[28:29], 0, v[216:217]
	s_add_i32 m0, s98, 0x400
	s_nop 0
	global_load_lds_dwordx4 v[4:5], off
	s_add_i32 m0, s98, 0x4400
	s_nop 0
	global_load_lds_dwordx4 v[2:3], off
	v_lshl_add_u64 v[2:3], s[28:29], 0, v[222:223]
	s_mov_b32 m0, s99
	s_nop 0
	global_load_lds_dwordx4 v[2:3], off
	s_branch .LBB0_853
.Lmla_y_pre:
	v_add_u32_e32 v249, s95, v237
	ds_read_b64_tr_b16 v[2:3], v249 offset:16384
	ds_read_b64_tr_b16 v[4:5], v249 offset:18432
	ds_read_b64_tr_b16 v[6:7], v249 offset:16896
	ds_read_b64_tr_b16 v[8:9], v249 offset:18944
	ds_read_b64_tr_b16 v[10:11], v249 offset:17408
	ds_read_b64_tr_b16 v[12:13], v249 offset:19456
	ds_read_b64_tr_b16 v[224:225], v249 offset:17920
	ds_read_b64_tr_b16 v[226:227], v249 offset:19968
	v_max3_f32 v245, v80, v81, v82
	v_max3_f32 v247, v83, v84, v85
	v_max3_f32 v245, v245, v86, v87
	v_max3_f32 v247, v247, v88, v89
	v_max3_f32 v245, v245, v90, v91
	v_max3_f32 v247, v247, v92, v93
	v_max3_f32 v245, v245, v94, v95
	v_max3_f32 v247, v247, v96, v97
	v_max3_f32 v245, v245, v98, v99
	v_max3_f32 v247, v247, v100, v101
	v_max3_f32 v245, v245, v102, v103
	v_max3_f32 v247, v247, v104, v105
	v_max3_f32 v245, v245, v106, v107
	v_max3_f32 v247, v247, v108, v109
	v_max3_f32 v245, v245, v110, v111
	v_lshl_add_u64 v[14:15], s[28:29], 0, v[218:219]
	s_mov_b32 m0, s98
	s_nop 0
	global_load_lds_dwordx4 v[14:15], off
	v_max_f32_e32 v245, v245, v247
	v_mov_b32_e32 v247, v245
	s_nop 1
	v_permlane32_swap_b32_e32 v245, v247
	s_nop 0
	v_max3_f32 v243, v244, v245, v247
	v_sub_f32_e32 v246, v244, v243
	v_sub_f32_e32 v80, v80, v243
	v_sub_f32_e32 v81, v81, v243
	v_sub_f32_e32 v82, v82, v243
	v_sub_f32_e32 v83, v83, v243
	v_sub_f32_e32 v84, v84, v243
	v_sub_f32_e32 v85, v85, v243
	v_sub_f32_e32 v86, v86, v243
	v_sub_f32_e32 v87, v87, v243
	v_exp_f32_e32 v246, v246
	v_exp_f32_e32 v80, v80
	v_exp_f32_e32 v81, v81
	v_exp_f32_e32 v82, v82
	v_exp_f32_e32 v83, v83
	v_exp_f32_e32 v84, v84
	v_exp_f32_e32 v85, v85
	v_exp_f32_e32 v86, v86
	v_exp_f32_e32 v87, v87
	v_lshl_add_u64 v[14:15], s[28:29], 0, v[220:221]
	s_add_i32 m0, s98, 0x4000
	v_lshl_add_u64 v[252:253], v[14:15], 0, s[100:101]
	global_load_lds_dwordx4 v[252:253], off
	v_pk_mul_f32 v[64:65], v[64:65], v[246:247] op_sel_hi:[1,0]
	v_pk_mul_f32 v[66:67], v[66:67], v[246:247] op_sel_hi:[1,0]
	v_pk_mul_f32 v[68:69], v[68:69], v[246:247] op_sel_hi:[1,0]
	v_pk_mul_f32 v[70:71], v[70:71], v[246:247] op_sel_hi:[1,0]
	v_pk_mul_f32 v[72:73], v[72:73], v[246:247] op_sel_hi:[1,0]
	v_pk_mul_f32 v[74:75], v[74:75], v[246:247] op_sel_hi:[1,0]
	v_pk_mul_f32 v[76:77], v[76:77], v[246:247] op_sel_hi:[1,0]
	v_pk_mul_f32 v[78:79], v[78:79], v[246:247] op_sel_hi:[1,0]
	v_add_f32_e32 v248, v80, v81
	v_add_f32_e32 v250, v82, v83
	v_add_f32_e32 v248, v248, v84
	v_add_f32_e32 v250, v250, v85
	v_add_f32_e32 v248, v248, v86
	v_add_f32_e32 v250, v250, v87
	v_cvt_pk_bf16_f32 v80, v80, v81
	v_cvt_pk_bf16_f32 v81, v82, v83
	v_cvt_pk_bf16_f32 v82, v84, v85
	v_cvt_pk_bf16_f32 v83, v86, v87
	v_pk_mul_f32 v[48:49], v[48:49], v[246:247] op_sel_hi:[1,0]
	v_pk_mul_f32 v[50:51], v[50:51], v[246:247] op_sel_hi:[1,0]
	v_pk_mul_f32 v[52:53], v[52:53], v[246:247] op_sel_hi:[1,0]
	v_pk_mul_f32 v[54:55], v[54:55], v[246:247] op_sel_hi:[1,0]
	v_pk_mul_f32 v[56:57], v[56:57], v[246:247] op_sel_hi:[1,0]
	v_pk_mul_f32 v[58:59], v[58:59], v[246:247] op_sel_hi:[1,0]
	v_pk_mul_f32 v[60:61], v[60:61], v[246:247] op_sel_hi:[1,0]
	v_pk_mul_f32 v[62:63], v[62:63], v[246:247] op_sel_hi:[1,0]
	s_waitcnt lgkmcnt(6)
	v_mfma_f32_32x32x16_bf16 v[64:79], v[2:5], v[80:83], v[64:79]
	ds_read_b64_tr_b16 v[2:3], v249 offset:20480
	ds_read_b64_tr_b16 v[4:5], v249 offset:22528
	v_pk_mul_f32 v[32:33], v[32:33], v[246:247] op_sel_hi:[1,0]
	v_pk_mul_f32 v[34:35], v[34:35], v[246:247] op_sel_hi:[1,0]
	v_pk_mul_f32 v[36:37], v[36:37], v[246:247] op_sel_hi:[1,0]
	v_pk_mul_f32 v[38:39], v[38:39], v[246:247] op_sel_hi:[1,0]
	v_pk_mul_f32 v[40:41], v[40:41], v[246:247] op_sel_hi:[1,0]
	v_pk_mul_f32 v[42:43], v[42:43], v[246:247] op_sel_hi:[1,0]
	v_pk_mul_f32 v[44:45], v[44:45], v[246:247] op_sel_hi:[1,0]
	v_pk_mul_f32 v[46:47], v[46:47], v[246:247] op_sel_hi:[1,0]
	v_lshl_add_u64 v[252:253], s[28:29], 0, v[216:217]
	s_add_i32 m0, s98, 0x400
	s_nop 0
	global_load_lds_dwordx4 v[252:253], off
	s_waitcnt lgkmcnt(6)
	v_mfma_f32_32x32x16_bf16 v[48:63], v[6:9], v[80:83], v[48:63]
	ds_read_b64_tr_b16 v[6:7], v249 offset:20992
	ds_read_b64_tr_b16 v[8:9], v249 offset:23040
	v_pk_mul_f32 v[16:17], v[16:17], v[246:247] op_sel_hi:[1,0]
	v_pk_mul_f32 v[18:19], v[18:19], v[246:247] op_sel_hi:[1,0]
	v_pk_mul_f32 v[20:21], v[20:21], v[246:247] op_sel_hi:[1,0]
	v_pk_mul_f32 v[22:23], v[22:23], v[246:247] op_sel_hi:[1,0]
	v_pk_mul_f32 v[24:25], v[24:25], v[246:247] op_sel_hi:[1,0]
	v_pk_mul_f32 v[26:27], v[26:27], v[246:247] op_sel_hi:[1,0]
	v_pk_mul_f32 v[28:29], v[28:29], v[246:247] op_sel_hi:[1,0]
	v_pk_mul_f32 v[30:31], v[30:31], v[246:247] op_sel_hi:[1,0]
	s_waitcnt lgkmcnt(6)
; DI unsigned pk2(float lo, float hi) { f32x2_t v = {lo, hi}; bf16x2_t b = __builtin_convertvector(v, bf16x2_t); return __builtin_bit_cast(unsigned, b); }
; #define MFMA32(a, b, c) __builtin_amdgcn_mfma_f32_32x32x16_bf16((a), (b), (c), 0, 0, 0)
; DI s16x4 vtr(const LAS unsigned char* p) { return __builtin_bit_cast(s16x4, __builtin_amdgcn_ds_read_tr16_b64_v4i16((LAS v4i16_t*)p)); }
; template <bool MLA>
; DI void attn_unit(LAS unsigned char* lds, const bf16* Qp, int qstride, const bf16* Kp, int kstride, const bf16* KRp, const bf16* Vp, int vstride,
;                   bf16* Op, int ostride, int t_lo, int t_hi, int qc, bool active, int wave, int lane) {
;     ...
;             float ps = 0.f;
; #pragma unroll
;             for (int i = 0; i < 16; ++i) { s0[i] = __builtin_amdgcn_exp2f(s0[i] - m_new); s1[i] = __builtin_amdgcn_exp2f(s1[i] - m_new); ps += s0[i] + s1[i]; }
;             l_run = l_run * alpha + ps;
; #pragma unroll
;             for (int d = 0; d < 4; ++d)
; #pragma unroll
;                 for (int i = 0; i < 16; ++i) o[d][i] *= alpha;
; #pragma unroll
;             for (int kt = 0; kt < 2; ++kt) {
; #pragma unroll
;                 for (int s = 0; s < 2; ++s) {
;                     u32x4 pw;
;                     if (kt == 0) { pw.x = pk2(s0[8 * s], s0[8 * s + 1]); pw.y = pk2(s0[8 * s + 2], s0[8 * s + 3]); pw.z = pk2(s0[8 * s + 4], s0[8 * s + 5]); pw.w = pk2(s0[8 * s + 6], s0[8 * s + 7]); }
;                     else { pw.x = pk2(s1[8 * s], s1[8 * s + 1]); pw.y = pk2(s1[8 * s + 2], s1[8 * s + 3]); pw.z = pk2(s1[8 * s + 4], s1[8 * s + 5]); pw.w = pk2(s1[8 * s + 6], s1[8 * s + 7]); }
;                     const bf16x8 pb = __builtin_bit_cast(bf16x8, pw);
; #pragma unroll
;                     for (int dt = 0; dt < 4; ++dt) {
;                         const s16x4 lo = vtr(buf + AT_V + ((4 * kt + 2 * s) * 4 + dt) * 512 + voff);
;                         const s16x4 hi = vtr(buf + AT_V + ((4 * kt + 2 * s + 1) * 4 + dt) * 512 + voff);
;                         const bf16x8 va = __builtin_shufflevector(lo, hi, 0, 1, 2, 3, 4, 5, 6, 7);
;                         o[dt] = MFMA32(va, pb, o[dt]);
;                     }
;                     __builtin_amdgcn_sched_barrier(0);
;                 }
;             }
	v_mfma_f32_32x32x16_bf16 v[32:47], v[10:13], v[80:83], v[32:47]
	ds_read_b64_tr_b16 v[10:11], v249 offset:21504
	ds_read_b64_tr_b16 v[12:13], v249 offset:23552
	v_sub_f32_e32 v88, v88, v243
	v_sub_f32_e32 v89, v89, v243
	v_sub_f32_e32 v90, v90, v243
	v_sub_f32_e32 v91, v91, v243
	v_sub_f32_e32 v92, v92, v243
	v_sub_f32_e32 v93, v93, v243
	v_sub_f32_e32 v94, v94, v243
	v_sub_f32_e32 v95, v95, v243
	v_exp_f32_e32 v88, v88
	v_exp_f32_e32 v89, v89
	s_waitcnt lgkmcnt(6)
	v_mfma_f32_32x32x16_bf16 v[16:31], v[224:227], v[80:83], v[16:31]
	ds_read_b64_tr_b16 v[224:225], v249 offset:22016
	ds_read_b64_tr_b16 v[226:227], v249 offset:24064
	v_exp_f32_e32 v90, v90
	v_exp_f32_e32 v91, v91
	v_exp_f32_e32 v92, v92
	v_exp_f32_e32 v93, v93
	v_exp_f32_e32 v94, v94
	v_exp_f32_e32 v95, v95
	v_lshl_add_u64 v[14:15], v[14:15], 0, s[44:45]
	s_add_i32 m0, s98, 0x4400
	s_nop 0
	global_load_lds_dwordx4 v[14:15], off
	v_sub_f32_e32 v96, v96, v243
	v_sub_f32_e32 v97, v97, v243
	v_sub_f32_e32 v98, v98, v243
	v_sub_f32_e32 v99, v99, v243
	v_sub_f32_e32 v100, v100, v243
	v_sub_f32_e32 v101, v101, v243
	v_sub_f32_e32 v102, v102, v243
	v_sub_f32_e32 v103, v103, v243
	v_add_f32_e32 v248, v248, v88
	v_add_f32_e32 v250, v250, v89
	v_add_f32_e32 v248, v248, v90
	v_add_f32_e32 v250, v250, v91
	v_add_f32_e32 v248, v248, v92
	v_add_f32_e32 v250, v250, v93
	v_add_f32_e32 v248, v248, v94
	v_add_f32_e32 v250, v250, v95
	v_cvt_pk_bf16_f32 v88, v88, v89
	v_cvt_pk_bf16_f32 v89, v90, v91
	v_cvt_pk_bf16_f32 v90, v92, v93
	v_cvt_pk_bf16_f32 v91, v94, v95
	v_exp_f32_e32 v96, v96
	s_waitcnt lgkmcnt(6)
	v_mfma_f32_32x32x16_bf16 v[64:79], v[2:5], v[88:91], v[64:79]
	ds_read_b64_tr_b16 v[2:3], v249 offset:24576
	ds_read_b64_tr_b16 v[4:5], v249 offset:26624
	v_exp_f32_e32 v97, v97
	v_exp_f32_e32 v98, v98
	s_waitcnt lgkmcnt(6)
	v_mfma_f32_32x32x16_bf16 v[48:63], v[6:9], v[88:91], v[48:63]
	ds_read_b64_tr_b16 v[6:7], v249 offset:25088
	ds_read_b64_tr_b16 v[8:9], v249 offset:27136
	v_exp_f32_e32 v99, v99
	v_exp_f32_e32 v100, v100
	v_lshl_add_u64 v[14:15], s[28:29], 0, v[222:223]
	s_mov_b32 m0, s99
	s_nop 0
	global_load_lds_dwordx4 v[14:15], off
	s_waitcnt lgkmcnt(6)
	v_mfma_f32_32x32x16_bf16 v[32:47], v[10:13], v[88:91], v[32:47]
	ds_read_b64_tr_b16 v[10:11], v249 offset:25600
	ds_read_b64_tr_b16 v[12:13], v249 offset:27648
	v_exp_f32_e32 v101, v101
	v_exp_f32_e32 v102, v102
	s_waitcnt lgkmcnt(6)
	v_mfma_f32_32x32x16_bf16 v[16:31], v[224:227], v[88:91], v[16:31]
	ds_read_b64_tr_b16 v[224:225], v249 offset:26112
	ds_read_b64_tr_b16 v[226:227], v249 offset:28160
	v_exp_f32_e32 v103, v103
	v_sub_f32_e32 v104, v104, v243
	v_sub_f32_e32 v105, v105, v243
	v_sub_f32_e32 v106, v106, v243
	v_sub_f32_e32 v107, v107, v243
	v_sub_f32_e32 v108, v108, v243
	v_sub_f32_e32 v109, v109, v243
	v_sub_f32_e32 v110, v110, v243
	v_sub_f32_e32 v111, v111, v243
	v_add_f32_e32 v248, v248, v96
	v_add_f32_e32 v250, v250, v97
	v_add_f32_e32 v248, v248, v98
	v_add_f32_e32 v250, v250, v99
	v_add_f32_e32 v248, v248, v100
	v_add_f32_e32 v250, v250, v101
	v_add_f32_e32 v248, v248, v102
	v_add_f32_e32 v250, v250, v103
	v_cvt_pk_bf16_f32 v96, v96, v97
	v_cvt_pk_bf16_f32 v97, v98, v99
	v_cvt_pk_bf16_f32 v98, v100, v101
	v_cvt_pk_bf16_f32 v99, v102, v103
	v_exp_f32_e32 v104, v104
	s_waitcnt lgkmcnt(6)
	v_mfma_f32_32x32x16_bf16 v[64:79], v[2:5], v[96:99], v[64:79]
	ds_read_b64_tr_b16 v[2:3], v249 offset:28672
	ds_read_b64_tr_b16 v[4:5], v249 offset:30720
	v_exp_f32_e32 v105, v105
	v_exp_f32_e32 v106, v106
	s_waitcnt lgkmcnt(6)
	v_mfma_f32_32x32x16_bf16 v[48:63], v[6:9], v[96:99], v[48:63]
	ds_read_b64_tr_b16 v[6:7], v249 offset:29184
	ds_read_b64_tr_b16 v[8:9], v249 offset:31232
	v_exp_f32_e32 v107, v107
	v_exp_f32_e32 v108, v108
	s_waitcnt lgkmcnt(6)
	v_mfma_f32_32x32x16_bf16 v[32:47], v[10:13], v[96:99], v[32:47]
	ds_read_b64_tr_b16 v[10:11], v249 offset:29696
	ds_read_b64_tr_b16 v[12:13], v249 offset:31744
	v_exp_f32_e32 v109, v109
	v_exp_f32_e32 v110, v110
	s_waitcnt lgkmcnt(6)
	v_mfma_f32_32x32x16_bf16 v[16:31], v[224:227], v[96:99], v[16:31]
	ds_read_b64_tr_b16 v[224:225], v249 offset:30208
	ds_read_b64_tr_b16 v[226:227], v249 offset:32256
	v_exp_f32_e32 v111, v111
	s_nop 0
	v_add_f32_e32 v248, v248, v104
	v_add_f32_e32 v250, v250, v105
	v_add_f32_e32 v248, v248, v106
	v_add_f32_e32 v250, v250, v107
	v_add_f32_e32 v248, v248, v108
	v_add_f32_e32 v250, v250, v109
	v_add_f32_e32 v248, v248, v110
	v_add_f32_e32 v250, v250, v111
	v_cvt_pk_bf16_f32 v104, v104, v105
	v_cvt_pk_bf16_f32 v105, v106, v107
	v_cvt_pk_bf16_f32 v106, v108, v109
	v_cvt_pk_bf16_f32 v107, v110, v111
	v_add_f32_e32 v248, v248, v250
	v_fmac_f32_e32 v248, v242, v246
	s_waitcnt lgkmcnt(6)
	v_mfma_f32_32x32x16_bf16 v[64:79], v[2:5], v[104:107], v[64:79]
	s_waitcnt lgkmcnt(4)
	v_mfma_f32_32x32x16_bf16 v[48:63], v[6:9], v[104:107], v[48:63]
	s_waitcnt lgkmcnt(2)
	v_mfma_f32_32x32x16_bf16 v[32:47], v[10:13], v[104:107], v[32:47]
	s_waitcnt lgkmcnt(0)
	v_mfma_f32_32x32x16_bf16 v[16:31], v[224:227], v[104:107], v[16:31]
	v_mov_b32_e32 v242, v248
	v_mov_b32_e32 v244, v243
	s_branch .Lmla_y_done

; #define AT_BAR() asm volatile("s_waitcnt lgkmcnt(0)\n\ts_barrier" ::: "memory")
; #define AT_WAITBAR(pre) do { if (pre) asm volatile("s_waitcnt vmcnt(%0) lgkmcnt(0)\n\ts_barrier" :: "i"(NP) : "memory"); else asm volatile("s_waitcnt vmcnt(0) lgkmcnt(0)\n\ts_barrier" ::: "memory"); } while (0)
; template <bool MLA>
; DI void attn_unit(LAS unsigned char* lds, const bf16* Qp, int qstride, const bf16* Kp, int kstride, const bf16* KRp, const bf16* Vp, int vstride,
;                   bf16* Op, int ostride, int t_lo, int t_hi, int qc, bool active, int wave, int lane) {
;     ...
;             }
;         }
;         if (!grp) AT_WAITBAR(pre); else AT_BAR();
;     }
.Lmla_y_done:
	s_mov_b64 s[58:59], -1
	s_and_b64 vcc, exec, s[12:13]
	s_cbranch_vccz .LBB0_854

; DI void p10_hn(const Args& a, int lane, int wave) {
;     float* rs2 = (float*)(a.ws + 32768); bf16* H16 = (bf16*)(a.ws + WS_H16);
;     const int gw = blockIdx.x * 8 + wave, nw = gridDim.x * 8;
;     for (int row = gw; row < MT; row += nw) {
;         float ss = 0.f;
.LBB0_1139:
	s_or_b64 exec, exec, s[0:1]
	s_cmp_lt_i32 s30, 11
	s_cselect_b64 s[0:1], -1, 0
	s_cmp_gt_i32 s31, 10
	s_cselect_b64 s[2:3], -1, 0
	s_and_b64 s[0:1], s[0:1], s[2:3]
	s_andn2_b64 vcc, exec, s[0:1]
	s_waitcnt lgkmcnt(0)
	s_barrier
	s_cbranch_vccnz .LBB0_1149
	s_lshl_b32 s0, s10, 3
	v_readlane_b32 s1, v254, 18
	s_add_i32 s0, s1, s0
	s_addk_i32 s0, 0x4000
	s_cmpk_gt_i32 s0, 0x41ff
	s_cbranch_scc1 .LBB0_1149
	v_mbcnt_lo_u32_b32 v0, -1, 0
	v_mbcnt_hi_u32_b32 v0, -1, v0
	v_and_b32_e32 v2, 64, v0
	v_add_u32_e32 v2, 64, v2
	v_xor_b32_e32 v3, 32, v0
	v_cmp_lt_i32_e32 vcc, v3, v2
	s_add_u32 s8, s28, 0x14b00000
	s_addc_u32 s9, s29, 0
	v_cndmask_b32_e32 v3, v0, v3, vcc
	v_lshlrev_b32_e32 v28, 2, v3
	v_xor_b32_e32 v3, 16, v0
	v_cmp_lt_i32_e32 vcc, v3, v2
	s_lshl_b32 s4, s34, 3
	s_add_u32 s11, s28, 0xdd00000
	v_cndmask_b32_e32 v3, v0, v3, vcc
	v_lshlrev_b32_e32 v29, 2, v3
	v_xor_b32_e32 v3, 8, v0
	v_cmp_lt_i32_e32 vcc, v3, v2
	s_addc_u32 s24, s29, 0
	s_ashr_i32 s1, s0, 31
	v_cndmask_b32_e32 v3, v0, v3, vcc
	v_lshlrev_b32_e32 v30, 2, v3
	v_xor_b32_e32 v3, 4, v0
	v_cmp_lt_i32_e32 vcc, v3, v2
	s_lshl_b64 s[12:13], s[0:1], 12
	s_ashr_i32 s5, s4, 31
	v_cndmask_b32_e32 v3, v0, v3, vcc
	v_lshlrev_b32_e32 v31, 2, v3
	v_xor_b32_e32 v3, 2, v0
	v_cmp_lt_i32_e32 vcc, v3, v2
	v_lshlrev_b32_e32 v4, 2, v160
	v_or_b32_e32 v12, 0x100, v160
	v_cndmask_b32_e32 v3, v0, v3, vcc
	v_lshlrev_b32_e32 v32, 2, v3
	v_xor_b32_e32 v3, 1, v0
	v_cmp_lt_i32_e32 vcc, v3, v2
	v_or_b32_e32 v16, 0x140, v160
	v_or_b32_e32 v20, 0x180, v160
	v_or_b32_e32 v24, 0x1c0, v160
	v_cndmask_b32_e32 v0, v0, v3, vcc
	v_lshl_or_b32 v2, v160, 4, s12
	v_mov_b32_e32 v3, s13
	s_lshl_b64 s[12:13], s[4:5], 12
	s_lshl_b64 s[14:15], s[0:1], 2
	v_or_b32_e32 v6, 0x100, v4
	v_or_b32_e32 v8, 0x200, v4
	v_or_b32_e32 v10, 0x300, v4
	v_lshlrev_b32_e32 v14, 2, v12
	v_lshlrev_b32_e32 v18, 2, v16
	v_lshlrev_b32_e32 v22, 2, v20
	v_lshlrev_b32_e32 v26, 2, v24
	s_add_u32 s25, s14, 0x8000
	s_mov_b32 s7, 0
	v_cmp_eq_u32_e64 s[2:3], 0, v160
	v_mov_b32_e32 v1, 0
	v_lshlrev_b32_e32 v33, 2, v0
	s_addc_u32 s36, s15, 0
	s_lshl_b64 s[14:15], s[4:5], 2
	v_lshlrev_b32_e32 v0, 4, v160
	s_mov_b32 s5, 0x400000
	s_mov_b32 s37, 0x800000
	s_mov_b32 s40, 0xc00000
	s_mov_b32 s41, 0x1000000
	s_mov_b32 s42, 0x1400000
	s_mov_b32 s43, 0x1800000
	s_mov_b32 s44, 0x1c00000
	v_lshlrev_b32_e32 v34, 1, v4
	v_lshlrev_b32_e32 v35, 1, v6
	v_lshlrev_b32_e32 v36, 1, v8
	v_lshlrev_b32_e32 v37, 1, v10
	v_lshlrev_b32_e32 v4, 4, v12
	v_lshlrev_b32_e32 v38, 1, v14
	v_lshlrev_b32_e32 v6, 4, v16
	v_lshlrev_b32_e32 v39, 1, v18
	v_lshlrev_b32_e32 v8, 4, v20
	v_lshlrev_b32_e32 v40, 1, v22
	v_lshlrev_b32_e32 v10, 4, v24
	v_lshlrev_b32_e32 v41, 1, v26
	v_mov_b32_e32 v42, 0x358637bd
	s_branch .LBB0_1143

; DI unsigned pk2(float lo, float hi) { f32x2_t v = {lo, hi}; bf16x2_t b = __builtin_convertvector(v, bf16x2_t); return __builtin_bit_cast(unsigned, b); }
; DI void unpack8(u32x4 w, float* f) { f[0] = bflo(w.x); f[1] = bfhi(w.x); f[2] = bflo(w.y); f[3] = bfhi(w.y); f[4] = bflo(w.z); f[5] = bfhi(w.z); f[6] = bflo(w.w); f[7] = bfhi(w.w); }
; DI void p10_hn(const Args& a, int lane, int wave) {
;     ...
;     for (int row = gw; row < MT; row += nw) {
;         float ss = 0.f;
;         if (row < MP) {
;             const u32x4* hr = (const u32x4*)(H16 + (size_t)row * 2048);
;             float t[4][8];
; #pragma unroll
;             for (int q = 0; q < 4; ++q) unpack8(hr[lane + 64 * q], t[q]);
; #pragma unroll
;             for (int q = 0; q < 4; ++q)
; #pragma unroll
;                 for (int e = 0; e < 8; ++e) ss += t[q][e] * t[q][e];
;         } else {
;             f32x4 v[8];
;             const float* xr = a.in[1] + (size_t)(row - MP) * 2048; const float* pr = (const float*)(a.ws + WS_PART1) + (size_t)(row - MP) * 2048;
; #pragma unroll
;             for (int i = 0; i < 8; ++i) { v[i] = ((const f32x4*)xr)[lane + 64 * i];
; #pragma unroll
;                 for (int k = 0; k < 8; ++k) v[i] += ((const f32x4*)(pr + (size_t)k * (MS * 2048)))[lane + 64 * i];
;                 ((f32x4*)(a.out + (size_t)row * 2048))[lane + 64 * i] = v[i];
;                 u32x2 w; w.x = pk2(v[i][0], v[i][1]); w.y = pk2(v[i][2], v[i][3]);
;                 *(u32x2*)(H16 + (size_t)row * 2048 + 4 * (lane + 64 * i)) = w;
;                 const float b0 = bflo(w.x), b1 = bfhi(w.x), b2 = bflo(w.y), b3 = bfhi(w.y);
;                 ss += b0 * b0 + b1 * b1 + b2 * b2 + b3 * b3; }
;         }
;         ss = wave_sum(ss);
;         if (lane == 0) rs2[row] = 1.0f / (ss * (1.0f / 2048.0f) + EPS);
.LBB0_1218:
	s_cmp_lt_u32 s10, 64
	s_cbranch_scc1 .Lrs2_skip
	v_lshlrev_b32_e32 v255, 4, v161
	ds_write_b128 v255, v[0:3]
	ds_write_b128 v255, v[4:7] offset:8192
	ds_write_b128 v255, v[8:11] offset:16384
	ds_write_b128 v255, v[12:15] offset:24576
	ds_write_b128 v255, v[16:19] offset:32768
	ds_write_b128 v255, v[20:23] offset:40960
	v_readlane_b32 s98, v254, 18
	s_sub_i32 s99, s10, 64
	s_lshl_b32 s99, s99, 3
	s_add_i32 s98, s98, s99
	v_lshlrev_b32_e32 v20, 4, v160
.Lrs2_loop:
	s_lshl_b32 s99, s98, 12
	s_add_u32 s100, s28, s99
	s_addc_u32 s101, s29, 0
	s_add_u32 s100, s100, 0x14b00000
	s_addc_u32 s101, s101, 0
	global_load_dwordx4 v[0:3], v20, s[100:101]
	global_load_dwordx4 v[4:7], v20, s[100:101] offset:1024
	global_load_dwordx4 v[8:11], v20, s[100:101] offset:2048
	global_load_dwordx4 v[12:15], v20, s[100:101] offset:3072
	s_lshl_b32 s99, s98, 2
	s_add_u32 s99, s99, 0x8000
	v_mov_b32_e32 v18, s99
	v_mov_b32_e32 v19, 0
	v_lshl_add_u64 v[18:19], s[28:29], 0, v[18:19]
	v_mov_b32_e32 v16, 0
	s_waitcnt vmcnt(3)
	v_lshlrev_b32_e32 v17, 16, v0
	v_and_b32_e32 v21, 0xffff0000, v0
	v_fmac_f32_e32 v16, v17, v17
	v_fmac_f32_e32 v16, v21, v21
	v_lshlrev_b32_e32 v17, 16, v1
	v_and_b32_e32 v21, 0xffff0000, v1
	v_fmac_f32_e32 v16, v17, v17
	v_fmac_f32_e32 v16, v21, v21
	v_lshlrev_b32_e32 v17, 16, v2
	v_and_b32_e32 v21, 0xffff0000, v2
	v_fmac_f32_e32 v16, v17, v17
	v_fmac_f32_e32 v16, v21, v21
	v_lshlrev_b32_e32 v17, 16, v3
	v_and_b32_e32 v21, 0xffff0000, v3
	v_fmac_f32_e32 v16, v17, v17
	v_fmac_f32_e32 v16, v21, v21
	s_waitcnt vmcnt(2)
	v_lshlrev_b32_e32 v17, 16, v4
	v_and_b32_e32 v21, 0xffff0000, v4
	v_fmac_f32_e32 v16, v17, v17
	v_fmac_f32_e32 v16, v21, v21
	v_lshlrev_b32_e32 v17, 16, v5
	v_and_b32_e32 v21, 0xffff0000, v5
	v_fmac_f32_e32 v16, v17, v17
	v_fmac_f32_e32 v16, v21, v21
	v_lshlrev_b32_e32 v17, 16, v6
	v_and_b32_e32 v21, 0xffff0000, v6
	v_fmac_f32_e32 v16, v17, v17
	v_fmac_f32_e32 v16, v21, v21
	v_lshlrev_b32_e32 v17, 16, v7
	v_and_b32_e32 v21, 0xffff0000, v7
	v_fmac_f32_e32 v16, v17, v17
	v_fmac_f32_e32 v16, v21, v21
	s_waitcnt vmcnt(1)
	v_lshlrev_b32_e32 v17, 16, v8
	v_and_b32_e32 v21, 0xffff0000, v8
	v_fmac_f32_e32 v16, v17, v17
	v_fmac_f32_e32 v16, v21, v21
	v_lshlrev_b32_e32 v17, 16, v9
	v_and_b32_e32 v21, 0xffff0000, v9
	v_fmac_f32_e32 v16, v17, v17
	v_fmac_f32_e32 v16, v21, v21
	v_lshlrev_b32_e32 v17, 16, v10
	v_and_b32_e32 v21, 0xffff0000, v10
	v_fmac_f32_e32 v16, v17, v17
	v_fmac_f32_e32 v16, v21, v21
	v_lshlrev_b32_e32 v17, 16, v11
	v_and_b32_e32 v21, 0xffff0000, v11
	v_fmac_f32_e32 v16, v17, v17
	v_fmac_f32_e32 v16, v21, v21
	s_waitcnt vmcnt(0)
	v_lshlrev_b32_e32 v17, 16, v12
	v_and_b32_e32 v21, 0xffff0000, v12
	v_fmac_f32_e32 v16, v17, v17
	v_fmac_f32_e32 v16, v21, v21
	v_lshlrev_b32_e32 v17, 16, v13
	v_and_b32_e32 v21, 0xffff0000, v13
	v_fmac_f32_e32 v16, v17, v17
	v_fmac_f32_e32 v16, v21, v21
	v_lshlrev_b32_e32 v17, 16, v14
	v_and_b32_e32 v21, 0xffff0000, v14
	v_fmac_f32_e32 v16, v17, v17
	v_fmac_f32_e32 v16, v21, v21
	v_lshlrev_b32_e32 v17, 16, v15
	v_and_b32_e32 v21, 0xffff0000, v15
	v_fmac_f32_e32 v16, v17, v17
	v_fmac_f32_e32 v16, v21, v21
	s_nop 1
	v_add_f32_dpp v16, v16, v16 quad_perm:[1,0,3,2] row_mask:0xf bank_mask:0xf
	s_nop 1
	v_add_f32_dpp v16, v16, v16 quad_perm:[2,3,0,1] row_mask:0xf bank_mask:0xf
	s_nop 1
	v_add_f32_dpp v16, v16, v16 row_half_mirror row_mask:0xf bank_mask:0xf
	s_nop 1
	v_add_f32_dpp v16, v16, v16 row_mirror row_mask:0xf bank_mask:0xf
	v_mov_b32_e32 v17, v16
	s_nop 1
	v_permlane16_swap_b32_e32 v16, v17
	s_nop 1
	v_add_f32_e32 v16, v16, v17
	v_mov_b32_e32 v17, v16
	s_nop 1
	v_permlane32_swap_b32_e32 v16, v17
	s_nop 1
	v_add_f32_e32 v16, v16, v17
	v_mov_b32_e32 v17, 0x358637bd
	v_fmac_f32_e32 v17, 0x3a000000, v16
	v_rcp_f32_e32 v21, v17
	s_nop 0
	v_fma_f32 v22, -v17, v21, 1.0
	v_fmac_f32_e32 v21, v22, v21
	v_cmp_eq_u32_e32 vcc, 0, v160
	s_and_saveexec_b64 s[100:101], vcc
	global_store_dword v[18:19], v21, off
	s_mov_b64 exec, s[100:101]
	s_addk_i32 s98, 0x600
	s_cmpk_lt_u32 s98, 0x4000
	s_cbranch_scc1 .Lrs2_loop
	ds_read_b128 v[0:3], v255
	ds_read_b128 v[4:7], v255 offset:8192
	ds_read_b128 v[8:11], v255 offset:16384
	ds_read_b128 v[12:15], v255 offset:24576
	ds_read_b128 v[16:19], v255 offset:32768
	ds_read_b128 v[20:23], v255 offset:40960
	s_waitcnt lgkmcnt(0)

; #define LAS __attribute__((address_space(3)))
; __global__ void __launch_bounds__(512, 2) mega_fwd(Args a) {
;     extern __shared__ __attribute__((aligned(16))) unsigned char lds_raw[];
;     LAS unsigned char* lds = (LAS unsigned char*)lds_raw;
;     cg::grid_group grid = cg::this_grid();
;     const int tid = threadIdx.x, lane = tid & 63, wave = __builtin_amdgcn_readfirstlane(tid >> 6);
	.amdhsa_kernel _Z8mega_fwd4Args
		.amdhsa_group_segment_fixed_size 0
		.amdhsa_private_segment_fixed_size 0
		.amdhsa_kernarg_size 472
		.amdhsa_user_sgpr_count 2
		.amdhsa_user_sgpr_dispatch_ptr 0
		.amdhsa_user_sgpr_queue_ptr 0
		.amdhsa_user_sgpr_kernarg_segment_ptr 1
		.amdhsa_user_sgpr_dispatch_id 0
		.amdhsa_user_sgpr_kernarg_preload_length 0
		.amdhsa_user_sgpr_kernarg_preload_offset 0
		.amdhsa_user_sgpr_private_segment_size 0
		.amdhsa_uses_dynamic_stack 0
		.amdhsa_enable_private_segment 0
		.amdhsa_system_sgpr_workgroup_id_x 1
		.amdhsa_system_sgpr_workgroup_id_y 0
		.amdhsa_system_sgpr_workgroup_id_z 0
		.amdhsa_system_sgpr_workgroup_info 0
		.amdhsa_system_vgpr_workitem_id 2
		.amdhsa_next_free_vgpr 256
		.amdhsa_next_free_sgpr 102
		.amdhsa_accum_offset 256
		.amdhsa_reserve_vcc 1
		.amdhsa_float_round_mode_32 0
		.amdhsa_float_round_mode_16_64 0
		.amdhsa_float_denorm_mode_32 3
		.amdhsa_float_denorm_mode_16_64 3
		.amdhsa_dx10_clamp 1
		.amdhsa_ieee_mode 1
		.amdhsa_fp16_overflow 0
		.amdhsa_tg_split 0
		.amdhsa_exception_fp_ieee_invalid_op 0
		.amdhsa_exception_fp_denorm_src 0
		.amdhsa_exception_fp_ieee_div_zero 0
		.amdhsa_exception_fp_ieee_overflow 0
		.amdhsa_exception_fp_ieee_underflow 0
		.amdhsa_exception_fp_ieee_inexact 0
		.amdhsa_exception_int_div_zero 0
	.end_amdhsa_kernel

; #define LAS __attribute__((address_space(3)))
; __global__ void __launch_bounds__(512, 2) mega_fwd(Args a) {
;     extern __shared__ __attribute__((aligned(16))) unsigned char lds_raw[];
;     LAS unsigned char* lds = (LAS unsigned char*)lds_raw;
;     cg::grid_group grid = cg::this_grid();
;     const int tid = threadIdx.x, lane = tid & 63, wave = __builtin_amdgcn_readfirstlane(tid >> 6);
amdhsa.kernels:
  - .agpr_count:     0
    .args:
      - .offset:         0
        .size:           216
        .value_kind:     by_value
      - .offset:         216
        .size:           4
        .value_kind:     hidden_block_count_x
      - .offset:         220
        .size:           4
        .value_kind:     hidden_block_count_y
      - .offset:         224
        .size:           4
        .value_kind:     hidden_block_count_z
      - .offset:         228
        .size:           2
        .value_kind:     hidden_group_size_x
      - .offset:         230
        .size:           2
        .value_kind:     hidden_group_size_y
      - .offset:         232
        .size:           2
        .value_kind:     hidden_group_size_z
      - .offset:         234
        .size:           2
        .value_kind:     hidden_remainder_x
      - .offset:         236
        .size:           2
        .value_kind:     hidden_remainder_y
      - .offset:         238
        .size:           2
        .value_kind:     hidden_remainder_z
      - .offset:         256
        .size:           8
        .value_kind:     hidden_global_offset_x
      - .offset:         264
        .size:           8
        .value_kind:     hidden_global_offset_y
      - .offset:         272
        .size:           8
        .value_kind:     hidden_global_offset_z
      - .offset:         280
        .size:           2
        .value_kind:     hidden_grid_dims
      - .offset:         304
        .size:           8
        .value_kind:     hidden_multigrid_sync_arg
      - .offset:         336
        .size:           4
        .value_kind:     hidden_dynamic_lds_size
    .group_segment_fixed_size: 0
    .kernarg_segment_align: 8
    .kernarg_segment_size: 472
    .language:       OpenCL C
    .language_version:
      - 2
      - 0
    .max_flat_workgroup_size: 512
    .name:           _Z8mega_fwd4Args
    .private_segment_fixed_size: 0
    .sgpr_count:     108
    .sgpr_spill_count: 48
    .symbol:         _Z8mega_fwd4Args.kd
    .uniform_work_group_size: 1
    .uses_dynamic_stack: false
    .vgpr_count:     256
    .vgpr_spill_count: 0
    .wavefront_size: 64
